# rwkv prep: 28 pairs of single-value cvt_pk+ds_write_b16 merged into packed cvt + ds_write_b16/d16_hi (-28 VALU per chunk), on top of v067
# speedup vs baseline: 1.0049x; 1.0008x over previous
.LBB0_637:
	v_cvt_f32_f16_e32 v69, v108
	v_cvt_f32_f16_sdwa v70, v108 dst_sel:DWORD dst_unused:UNUSED_PAD src0_sel:WORD_1
	v_cvt_f32_f16_sdwa v218, v110 dst_sel:DWORD dst_unused:UNUSED_PAD src0_sel:WORD_1
	v_cvt_f32_f16_sdwa v72, v109 dst_sel:DWORD dst_unused:UNUSED_PAD src0_sel:WORD_1
	v_add_f32_e32 v69, 0, v69
	v_mul_f32_e32 v74, 0x3fb8aa3b, v69
	v_exp_f32_e32 v74, v74
	v_mul_f32_e32 v76, v218, v70
	v_add_f32_e32 v70, -1.0, v70
	v_cvt_f32_f16_e32 v73, v110
	v_fma_f32 v70, v151, v70, 1.0
	v_mul_f32_e32 v70, v70, v72
	v_mul_f32_e32 v75, 0xbfb8aa3b, v69
	v_mul_f32_e32 v70, v74, v70
	v_cvt_f32_f16_e32 v71, v109
	v_exp_f32_e32 v75, v75
	v_cvt_pk_bf16_f32 v70, v70, v73
	ds_write_b16 v165, v70
	ds_write_b16_d16_hi v166, v70
	v_cvt_f32_f16_e32 v70, v66
	v_mul_f32_e32 v71, v75, v71
	v_mul_f32_e32 v76, v76, v74
	v_cvt_pk_bf16_f32 v71, v71, s0
	v_cvt_f32_f16_sdwa v66, v66 dst_sel:DWORD dst_unused:UNUSED_PAD src0_sel:WORD_1
	v_cvt_f32_f16_e32 v72, v68
	v_cvt_f32_f16_sdwa v68, v68 dst_sel:DWORD dst_unused:UNUSED_PAD src0_sel:WORD_1
	ds_write_b16 v163, v71
	v_cvt_pk_bf16_f32 v71, v76, s0
	v_add_f32_e32 v69, v69, v70
	ds_write_b16 v164, v71
	v_cvt_f32_f16_e32 v71, v67
	v_cvt_f32_f16_sdwa v67, v67 dst_sel:DWORD dst_unused:UNUSED_PAD src0_sel:WORD_1
	v_mul_f32_e32 v73, 0x3fb8aa3b, v69
	v_exp_f32_e32 v73, v73
	v_mul_f32_e64 v234, v75, -v68
	v_mul_f32_e32 v68, v68, v66
	v_add_f32_e32 v66, -1.0, v66
	v_fma_f32 v66, v151, v66, 1.0
	v_mul_f32_e32 v70, 0xbfb8aa3b, v69
	v_mul_f32_e32 v66, v66, v67
	v_exp_f32_e32 v70, v70
	v_mul_f32_e32 v66, v73, v66
	v_cvt_pk_bf16_f32 v66, v66, v72
	ds_write_b16 v164, v66 offset:2448
	ds_write_b16_d16_hi v166, v66 offset:144
	v_cvt_f32_f16_e32 v66, v63
	v_mul_f32_e32 v67, v70, v71
	v_mul_f32_e32 v68, v68, v73
	v_cvt_pk_bf16_f32 v67, v67, s0
	ds_write_b16 v155, v67 offset:2448
	v_cvt_pk_bf16_f32 v67, v68, s0
	v_cvt_f32_f16_sdwa v63, v63 dst_sel:DWORD dst_unused:UNUSED_PAD src0_sel:WORD_1
	v_cvt_f32_f16_e32 v68, v65
	v_cvt_f32_f16_sdwa v65, v65 dst_sel:DWORD dst_unused:UNUSED_PAD src0_sel:WORD_1
	v_cvt_pk_bf16_f32 v71, v234, s0
	v_add_f32_e32 v66, v69, v66
	ds_write_b16 v155, v71 offset:144
	ds_write_b16 v164, v67 offset:144
	v_cvt_f32_f16_e32 v67, v64
	v_cvt_f32_f16_sdwa v64, v64 dst_sel:DWORD dst_unused:UNUSED_PAD src0_sel:WORD_1
	v_mul_f32_e32 v71, 0x3fb8aa3b, v66
	v_exp_f32_e32 v71, v71
	v_mul_f32_e64 v241, v70, -v65
	v_mul_f32_e32 v65, v65, v63
	v_add_f32_e32 v63, -1.0, v63
	v_fma_f32 v63, v151, v63, 1.0
	v_mul_f32_e32 v69, 0xbfb8aa3b, v66
	v_mul_f32_e32 v63, v63, v64
	v_exp_f32_e32 v69, v69
	v_mul_f32_e32 v63, v63, v71
	v_cvt_pk_bf16_f32 v63, v63, v68
	ds_write_b16 v164, v63 offset:2592
	ds_write_b16_d16_hi v166, v63 offset:288
	v_cvt_f32_f16_e32 v63, v60
	v_mul_f32_e32 v64, v69, v67
	v_mul_f32_e32 v65, v65, v71
	v_cvt_pk_bf16_f32 v64, v64, s0
	ds_write_b16 v155, v64 offset:2592
	v_cvt_pk_bf16_f32 v64, v65, s0
	v_cvt_f32_f16_sdwa v60, v60 dst_sel:DWORD dst_unused:UNUSED_PAD src0_sel:WORD_1
	v_cvt_f32_f16_e32 v65, v62
	v_cvt_f32_f16_sdwa v62, v62 dst_sel:DWORD dst_unused:UNUSED_PAD src0_sel:WORD_1
	v_cvt_pk_bf16_f32 v67, v241, s0
	v_add_f32_e32 v63, v66, v63
	ds_write_b16 v155, v67 offset:288
	ds_write_b16 v164, v64 offset:288
	v_cvt_f32_f16_e32 v64, v61
	v_cvt_f32_f16_sdwa v61, v61 dst_sel:DWORD dst_unused:UNUSED_PAD src0_sel:WORD_1
	v_mul_f32_e32 v67, 0x3fb8aa3b, v63
	v_exp_f32_e32 v67, v67
	v_mul_f32_e64 v235, v69, -v62
	v_mul_f32_e32 v62, v62, v60
	v_add_f32_e32 v60, -1.0, v60
	v_fma_f32 v60, v151, v60, 1.0
	v_mul_f32_e32 v66, 0xbfb8aa3b, v63
	v_mul_f32_e32 v60, v60, v61
	v_exp_f32_e32 v66, v66
	v_mul_f32_e32 v60, v60, v67
	v_cvt_pk_bf16_f32 v60, v60, v65
	ds_write_b16 v164, v60 offset:2736
	ds_write_b16_d16_hi v166, v60 offset:432
	v_cvt_f32_f16_e32 v60, v9
	v_mul_f32_e32 v61, v66, v64
	v_mul_f32_e32 v62, v62, v67
	v_cvt_pk_bf16_f32 v61, v61, s0
	ds_write_b16 v155, v61 offset:2736
	v_cvt_pk_bf16_f32 v61, v62, s0
	v_cvt_f32_f16_sdwa v9, v9 dst_sel:DWORD dst_unused:UNUSED_PAD src0_sel:WORD_1
	v_cvt_f32_f16_e32 v62, v11
	v_cvt_f32_f16_sdwa v11, v11 dst_sel:DWORD dst_unused:UNUSED_PAD src0_sel:WORD_1
	v_cvt_pk_bf16_f32 v64, v235, s0
	v_add_f32_e32 v60, v63, v60
	ds_write_b16 v155, v64 offset:432
	ds_write_b16 v164, v61 offset:432
	v_cvt_f32_f16_e32 v61, v10
	v_cvt_f32_f16_sdwa v10, v10 dst_sel:DWORD dst_unused:UNUSED_PAD src0_sel:WORD_1
	v_mul_f32_e32 v64, 0x3fb8aa3b, v60
	v_exp_f32_e32 v64, v64
	v_mul_f32_e64 v244, v66, -v11
	v_mul_f32_e32 v11, v11, v9
	v_add_f32_e32 v9, -1.0, v9
	v_fma_f32 v9, v151, v9, 1.0
	v_mul_f32_e32 v63, 0xbfb8aa3b, v60
	v_mul_f32_e32 v9, v9, v10
	v_exp_f32_e32 v63, v63
	v_mul_f32_e32 v9, v9, v64
	v_cvt_pk_bf16_f32 v9, v9, v62
	ds_write_b16 v164, v9 offset:2880
	ds_write_b16_d16_hi v166, v9 offset:576
	v_cvt_f32_f16_e32 v9, v6
	v_mul_f32_e32 v10, v63, v61
	v_mul_f32_e32 v11, v11, v64
	v_cvt_pk_bf16_f32 v10, v10, s0
	ds_write_b16 v155, v10 offset:2880
	v_cvt_pk_bf16_f32 v10, v11, s0
	v_cvt_f32_f16_sdwa v6, v6 dst_sel:DWORD dst_unused:UNUSED_PAD src0_sel:WORD_1
	v_cvt_f32_f16_e32 v11, v8
	v_cvt_f32_f16_sdwa v8, v8 dst_sel:DWORD dst_unused:UNUSED_PAD src0_sel:WORD_1
	v_cvt_pk_bf16_f32 v61, v244, s0
	v_add_f32_e32 v9, v60, v9
	ds_write_b16 v155, v61 offset:576
	ds_write_b16 v164, v10 offset:576
	v_cvt_f32_f16_e32 v10, v7
	v_cvt_f32_f16_sdwa v7, v7 dst_sel:DWORD dst_unused:UNUSED_PAD src0_sel:WORD_1
	v_mul_f32_e32 v61, 0x3fb8aa3b, v9
	v_exp_f32_e32 v61, v61
	v_mul_f32_e64 v247, v63, -v8
	v_mul_f32_e32 v8, v8, v6
	v_add_f32_e32 v6, -1.0, v6
	v_fma_f32 v6, v151, v6, 1.0
	v_mul_f32_e32 v60, 0xbfb8aa3b, v9
	v_mul_f32_e32 v6, v6, v7
	v_exp_f32_e32 v60, v60
	v_mul_f32_e32 v6, v6, v61
	v_cvt_pk_bf16_f32 v6, v6, v11
	ds_write_b16 v164, v6 offset:3024
	ds_write_b16_d16_hi v166, v6 offset:720
	v_cvt_f32_f16_e32 v6, v3
	v_mul_f32_e32 v7, v60, v10
	v_mul_f32_e32 v8, v8, v61
	v_cvt_pk_bf16_f32 v7, v7, s0
	ds_write_b16 v155, v7 offset:3024
	v_cvt_pk_bf16_f32 v7, v8, s0
	v_cvt_f32_f16_sdwa v3, v3 dst_sel:DWORD dst_unused:UNUSED_PAD src0_sel:WORD_1
	v_cvt_f32_f16_e32 v8, v5
	v_cvt_f32_f16_sdwa v5, v5 dst_sel:DWORD dst_unused:UNUSED_PAD src0_sel:WORD_1
	v_cvt_pk_bf16_f32 v10, v247, s0
	v_add_f32_e32 v6, v9, v6
	ds_write_b16 v155, v10 offset:720
	ds_write_b16 v164, v7 offset:720
	v_cvt_f32_f16_e32 v7, v4
	v_cvt_f32_f16_sdwa v4, v4 dst_sel:DWORD dst_unused:UNUSED_PAD src0_sel:WORD_1
	v_mul_f32_e32 v10, 0x3fb8aa3b, v6
	v_exp_f32_e32 v10, v10
	v_mul_f32_e64 v249, v60, -v5
	v_mul_f32_e32 v5, v5, v3
	v_add_f32_e32 v3, -1.0, v3
	v_fma_f32 v3, v151, v3, 1.0
	v_mul_f32_e32 v9, 0xbfb8aa3b, v6
	v_mul_f32_e32 v3, v3, v4
	v_exp_f32_e32 v9, v9
	v_mul_f32_e32 v3, v3, v10
	v_cvt_pk_bf16_f32 v3, v3, v8
	ds_write_b16 v164, v3 offset:3168
	ds_write_b16_d16_hi v166, v3 offset:864
	v_cvt_f32_f16_e32 v3, v0
	v_mul_f32_e32 v4, v9, v7
	v_mul_f32_e32 v5, v5, v10
	v_cvt_pk_bf16_f32 v4, v4, s0
	ds_write_b16 v155, v4 offset:3168
	v_cvt_pk_bf16_f32 v4, v5, s0
	v_cvt_f32_f16_sdwa v0, v0 dst_sel:DWORD dst_unused:UNUSED_PAD src0_sel:WORD_1
	v_cvt_f32_f16_e32 v5, v2
	v_cvt_f32_f16_sdwa v2, v2 dst_sel:DWORD dst_unused:UNUSED_PAD src0_sel:WORD_1
	v_cvt_pk_bf16_f32 v7, v249, s0
	v_add_f32_e32 v3, v6, v3
	ds_write_b16 v155, v7 offset:864
	ds_write_b16 v164, v4 offset:864
	v_cvt_f32_f16_e32 v4, v1
	v_cvt_f32_f16_sdwa v1, v1 dst_sel:DWORD dst_unused:UNUSED_PAD src0_sel:WORD_1
	v_mul_f32_e32 v7, 0x3fb8aa3b, v3
	v_exp_f32_e32 v7, v7
	v_mul_f32_e64 v239, v9, -v2
	v_mul_f32_e32 v2, v2, v0
	v_add_f32_e32 v0, -1.0, v0
	v_mul_f32_e32 v6, 0xbfb8aa3b, v3
	v_fma_f32 v0, v151, v0, 1.0
	v_exp_f32_e32 v6, v6
	v_mul_f32_e32 v0, v0, v1
	v_mul_f32_e32 v0, v0, v7
	v_cvt_pk_bf16_f32 v0, v0, s0
	ds_write_b16 v164, v0 offset:3312
	v_cvt_pk_bf16_f32 v0, v5, s0
	v_mul_f32_e32 v1, v6, v4
	ds_write_b16 v166, v0 offset:1008
	s_waitcnt vmcnt(47)
	v_cvt_f32_f16_e32 v0, v59
	v_mul_f32_e32 v2, v2, v7
	v_cvt_pk_bf16_f32 v1, v1, v2
	ds_write_b16 v155, v1 offset:3312
	ds_write_b16_d16_hi v164, v1 offset:1008
	s_waitcnt vmcnt(46)
	v_cvt_f32_f16_e32 v1, v58
	s_waitcnt vmcnt(42)
	v_cvt_f32_f16_e32 v7, v51
	v_cvt_pk_bf16_f32 v4, v239, s0
	v_add_f32_e32 v0, v3, v0
	ds_write_b16 v155, v4 offset:1008
	v_cvt_f32_f16_e32 v4, v53
	v_mul_f32_e32 v8, 0x3fb8aa3b, v0
	v_exp_f32_e32 v8, v8
	v_mul_f32_e64 v242, v6, -v7
	v_mul_f32_e32 v6, v7, v1
	v_add_f32_e32 v1, -1.0, v1
	v_cvt_f32_f16_e32 v5, v57
	v_mul_f32_e32 v3, 0xbfb8aa3b, v0
	v_fma_f32 v1, v151, v1, 1.0
	v_cvt_f32_f16_e32 v2, v55
	v_exp_f32_e32 v3, v3
	v_mul_f32_e32 v1, v1, v4
	v_mul_f32_e32 v1, v1, v8
	v_cvt_pk_bf16_f32 v1, v1, s0
	ds_write_b16 v170, v1
	v_cvt_pk_bf16_f32 v1, v5, s0
	v_mul_f32_e32 v2, v3, v2
	ds_write_b16 v171, v1
	s_waitcnt vmcnt(41)
	v_cvt_f32_f16_e32 v1, v50
	v_mul_f32_e32 v6, v6, v8
	v_cvt_pk_bf16_f32 v2, v2, v6
	ds_write_b16 v168, v2
	ds_write_b16_d16_hi v169, v2
	s_waitcnt vmcnt(40)
	v_cvt_f32_f16_e32 v2, v47
	s_waitcnt vmcnt(36)
	v_cvt_f32_f16_e32 v7, v49
	v_add_f32_e32 v0, v0, v1
	v_cvt_f32_f16_e32 v5, v52
	v_mul_f32_e32 v8, 0x3fb8aa3b, v0
	v_exp_f32_e32 v8, v8
	v_mul_f32_e64 v246, v3, -v7
	v_mul_f32_e32 v3, v7, v2
	v_add_f32_e32 v2, -1.0, v2
	v_cvt_f32_f16_e32 v6, v56
	v_fma_f32 v2, v151, v2, 1.0
	v_mul_f32_e32 v2, v2, v5
	v_mul_f32_e32 v2, v2, v8
	v_cvt_pk_bf16_f32 v2, v2, v6
	ds_write_b16 v164, v2 offset:3600
	ds_write_b16_d16_hi v166, v2 offset:1296
	s_waitcnt vmcnt(35)
	v_cvt_f32_f16_e32 v2, v48
	v_mul_f32_e32 v3, v3, v8
	v_cvt_pk_bf16_f32 v4, v242, s0
	v_mul_f32_e32 v1, 0xbfb8aa3b, v0
	v_cvt_pk_bf16_f32 v3, v3, s0
	ds_write_b16 v167, v4
	v_cvt_f32_f16_e32 v4, v54
	v_exp_f32_e32 v1, v1
	ds_write_b16 v164, v3 offset:1296
	s_waitcnt vmcnt(34)
	v_cvt_f32_f16_e32 v3, v45
	s_waitcnt vmcnt(30)
	v_cvt_f32_f16_e32 v7, v46
	v_add_f32_e32 v0, v0, v2
	v_cvt_pk_bf16_f32 v5, v246, s0
	v_mul_f32_e32 v8, 0x3fb8aa3b, v0
	ds_write_b16 v155, v5 offset:1296
	v_cvt_f32_f16_e32 v5, v44
	v_exp_f32_e32 v8, v8
	v_mul_f32_e32 v4, v1, v4
	v_mul_f32_e64 v248, v1, -v7
	v_mul_f32_e32 v1, v7, v3
	v_add_f32_e32 v3, -1.0, v3
	v_cvt_f32_f16_e32 v6, v43
	v_fma_f32 v3, v151, v3, 1.0
	v_mul_f32_e32 v1, v1, v8
	v_mul_f32_e32 v3, v3, v5
	v_mul_f32_e32 v3, v3, v8
	v_cvt_pk_bf16_f32 v1, v1, v3
	ds_write_b16 v164, v1 offset:1440
	ds_write_b16_d16_hi v164, v1 offset:3744
	v_cvt_pk_bf16_f32 v1, v6, s0
	ds_write_b16 v166, v1 offset:1440
	s_waitcnt vmcnt(29)
	v_cvt_f32_f16_e32 v1, v39
	v_cvt_pk_bf16_f32 v4, v4, s0
	v_mul_f32_e32 v2, 0xbfb8aa3b, v0
	ds_write_b16 v155, v4 offset:3600
	v_cvt_f32_f16_e32 v4, v34
	v_exp_f32_e32 v2, v2
	s_waitcnt vmcnt(28)
	v_cvt_f32_f16_e32 v3, v36
	s_waitcnt vmcnt(24)
	v_cvt_f32_f16_e32 v7, v28
	v_add_f32_e32 v0, v0, v1
	v_cvt_pk_bf16_f32 v5, v248, s0
	v_mul_f32_e32 v8, 0x3fb8aa3b, v0
	ds_write_b16 v155, v5 offset:1440
	v_cvt_f32_f16_e32 v5, v31
	v_exp_f32_e32 v8, v8
	v_mul_f32_e32 v4, v2, v4
	v_mul_f32_e64 v225, v2, -v7
	v_mul_f32_e32 v2, v7, v3
	v_add_f32_e32 v3, -1.0, v3
	v_cvt_f32_f16_e32 v6, v35
	v_fma_f32 v3, v151, v3, 1.0
	v_mul_f32_e32 v2, v2, v8
	v_mul_f32_e32 v3, v3, v5
	v_mul_f32_e32 v3, v3, v8
	v_cvt_pk_bf16_f32 v2, v2, v3
	ds_write_b16 v164, v2 offset:1584
	ds_write_b16_d16_hi v164, v2 offset:3888
	v_cvt_pk_bf16_f32 v2, v6, s0
	ds_write_b16 v166, v2 offset:1584
	s_waitcnt vmcnt(23)
	v_cvt_f32_f16_e32 v2, v42
	v_cvt_pk_bf16_f32 v4, v4, s0
	v_mul_f32_e32 v1, 0xbfb8aa3b, v0
	ds_write_b16 v155, v4 offset:3744
	v_cvt_f32_f16_e32 v4, v32
	v_exp_f32_e32 v1, v1
	s_waitcnt vmcnt(22)
; #define LAS __attribute__((address_space(3)))
; #define LDS_WAIT() asm volatile("s_waitcnt lgkmcnt(0)" ::: "memory")
; #define MFMA32(a, b, c) __builtin_amdgcn_mfma_f32_32x32x16_bf16((a), (b), (c), 0, 0, 0)
; __device__ __forceinline__ unsigned lds_u16(const LAS bf16* p) { return (unsigned)*p; }
; __device__ __forceinline__ void phase_rwkv_fused(const Frame& F, const Args& a, int l) {
;     ...
; #pragma unroll
;         for (int vt = 0; vt < 2; ++vt) { v4u w;
; #pragma unroll
;             for (int q = 0; q < 4; ++q) w[q] = lds_u16(VL + (8 * hh + 2 * q) * LDA + 32 * vt + li) | (lds_u16(VL + (8 * hh + 2 * q + 1) * LDA + 32 * vt + li) << 16);
;             frv[vt] = w; }
;         f32x16 g;
; #pragma unroll
;         for (int e = 0; e < 16; ++e) g[e] = 0.f;
; #pragma unroll
;         for (int ks = 0; ks < 4; ++ks) { const bf16x8 af = *(const LAS bf16x8*)(AR + li * LDA + 16 * ks + 8 * hh); const bf16x8 bf = *(const LAS bf16x8*)(BK + li * LDA + 16 * ks + 8 * hh); g = MFMA32(af, bf, g); }
;         LDS_WAIT(); asm volatile("" ::: "memory");
; #pragma unroll
;         for (int e = 0; e < 16; ++e) GL[((e & 3) + 8 * (e >> 2) + 4 * hh) * GLD + li] = g[e];
	v_cvt_f32_f16_e32 v3, v41
	s_waitcnt vmcnt(18)
	v_cvt_f32_f16_e32 v7, v33
	v_add_f32_e32 v0, v0, v2
	v_cvt_pk_bf16_f32 v5, v225, s0
	v_mul_f32_e32 v8, 0x3fb8aa3b, v0
	ds_write_b16 v155, v5 offset:1584
	v_cvt_f32_f16_e32 v5, v37
	v_exp_f32_e32 v8, v8
	v_mul_f32_e32 v4, v1, v4
	v_mul_f32_e64 v226, v1, -v7
	v_mul_f32_e32 v1, v3, v7
	v_add_f32_e32 v3, -1.0, v3
	v_cvt_f32_f16_e32 v6, v40
	v_fma_f32 v3, v151, v3, 1.0
	v_mul_f32_e32 v1, v1, v8
	v_mul_f32_e32 v3, v3, v5
	v_mul_f32_e32 v3, v3, v8
	v_cvt_pk_bf16_f32 v1, v1, v3
	ds_write_b16 v164, v1 offset:1728
	ds_write_b16_d16_hi v164, v1 offset:4032
	v_cvt_pk_bf16_f32 v1, v6, s0
	ds_write_b16 v166, v1 offset:1728
	s_waitcnt vmcnt(17)
	v_cvt_f32_f16_e32 v1, v23
	v_cvt_pk_bf16_f32 v4, v4, s0
	v_mul_f32_e32 v2, 0xbfb8aa3b, v0
	ds_write_b16 v155, v4 offset:3888
	v_cvt_f32_f16_e32 v4, v38
	v_exp_f32_e32 v2, v2
	s_waitcnt vmcnt(16)
	v_cvt_f32_f16_e32 v3, v29
	s_waitcnt vmcnt(12)
	v_cvt_f32_f16_e32 v7, v30
	v_add_f32_e32 v0, v0, v1
	v_cvt_pk_bf16_f32 v5, v226, s0
	v_mul_f32_e32 v8, 0x3fb8aa3b, v0
	ds_write_b16 v155, v5 offset:1728
	v_cvt_f32_f16_e32 v5, v24
	v_exp_f32_e32 v8, v8
	v_mul_f32_e32 v4, v2, v4
	v_mul_f32_e64 v229, v2, -v7
	v_mul_f32_e32 v2, v3, v7
	v_add_f32_e32 v3, -1.0, v3
	v_cvt_f32_f16_e32 v6, v27
	v_fma_f32 v3, v151, v3, 1.0
	v_mul_f32_e32 v2, v2, v8
	v_mul_f32_e32 v3, v3, v5
	v_mul_f32_e32 v3, v3, v8
	v_cvt_pk_bf16_f32 v2, v2, v3
	ds_write_b16 v164, v2 offset:1872
	ds_write_b16_d16_hi v164, v2 offset:4176
	v_cvt_pk_bf16_f32 v2, v6, s0
	ds_write_b16 v166, v2 offset:1872
	s_waitcnt vmcnt(11)
	v_cvt_f32_f16_e32 v2, v22
	v_cvt_pk_bf16_f32 v4, v4, s0
	v_mul_f32_e32 v1, 0xbfb8aa3b, v0
	ds_write_b16 v155, v4 offset:4032
	v_cvt_f32_f16_e32 v4, v25
	v_exp_f32_e32 v1, v1
	s_waitcnt vmcnt(10)
	v_cvt_f32_f16_e32 v3, v20
	s_waitcnt vmcnt(6)
	v_cvt_f32_f16_e32 v7, v19
	v_add_f32_e32 v0, v0, v2
	v_cvt_pk_bf16_f32 v5, v229, s0
	v_mul_f32_e32 v8, 0x3fb8aa3b, v0
	ds_write_b16 v155, v5 offset:1872
	v_cvt_f32_f16_e32 v5, v15
	v_exp_f32_e32 v8, v8
	v_mul_f32_e32 v4, v1, v4
	v_mul_f32_e64 v231, v1, -v7
	v_mul_f32_e32 v1, v3, v7
	v_add_f32_e32 v3, -1.0, v3
	v_cvt_f32_f16_e32 v6, v26
	v_fma_f32 v3, v151, v3, 1.0
	v_mul_f32_e32 v1, v1, v8
	v_mul_f32_e32 v3, v3, v5
	v_mul_f32_e32 v3, v3, v8
	v_cvt_pk_bf16_f32 v1, v1, v3
	ds_write_b16 v164, v1 offset:2016
	ds_write_b16_d16_hi v164, v1 offset:4320
	v_cvt_pk_bf16_f32 v1, v6, s0
	v_cvt_pk_bf16_f32 v4, v4, s0
	v_mul_f32_e32 v2, 0xbfb8aa3b, v0
	ds_write_b16 v166, v1 offset:2016
	s_waitcnt vmcnt(5)
	v_cvt_f32_f16_e32 v1, v21
	ds_write_b16 v155, v4 offset:4176
	v_cvt_f32_f16_e32 v4, v16
	v_exp_f32_e32 v2, v2
	s_waitcnt vmcnt(4)
	v_cvt_f32_f16_e32 v3, v18
	s_waitcnt vmcnt(0)
	v_cvt_f32_f16_e32 v7, v12
	v_cvt_pk_bf16_f32 v5, v231, s0
	v_add_f32_e32 v0, v0, v1
	v_mul_f32_e32 v4, v2, v4
	ds_write_b16 v155, v5 offset:2016
	v_cvt_f32_f16_e32 v5, v13
	v_mul_f32_e32 v1, 0xbfb8aa3b, v0
	v_mul_f32_e32 v0, 0x3fb8aa3b, v0
	v_cvt_pk_bf16_f32 v4, v4, s0
	v_exp_f32_e32 v0, v0
	ds_write_b16 v155, v4 offset:4320
	v_cvt_f32_f16_e32 v4, v14
	v_exp_f32_e32 v194, v1
	v_mul_f32_e64 v219, v2, -v7
	v_add_f32_e32 v2, -1.0, v3
	v_cvt_f32_f16_e32 v6, v17
	v_fma_f32 v2, v151, v2, 1.0
	v_mul_f32_e32 v1, v3, v7
	v_mul_f32_e32 v2, v2, v5
	v_mul_f32_e32 v1, v1, v0
	v_mul_f32_e32 v0, v2, v0
	v_mul_f32_e32 v2, v194, v4
	v_cvt_pk_bf16_f32 v0, v0, s0
	v_cvt_pk_bf16_f32 v230, -v218, s0
	v_cvt_pk_bf16_f32 v3, v219, s0
	v_cvt_pk_bf16_f32 v2, v2, s0
	v_cvt_pk_bf16_f32 v1, v1, s0
	ds_write_b16 v164, v0 offset:4464
	v_cvt_pk_bf16_f32 v0, v6, s0
	ds_write_b16 v155, v230
	ds_write_b16 v155, v3 offset:2160
	ds_write_b16 v155, v2 offset:4464
	ds_write_b16 v164, v1 offset:2160
	ds_write_b16 v166, v0 offset:2160
	s_waitcnt lgkmcnt(0)
	ds_read_b128 v[0:3], v152
	ds_read_b128 v[4:7], v153
	ds_read_b128 v[16:19], v152 offset:32
	ds_read_b128 v[20:23], v153 offset:32
	s_waitcnt lgkmcnt(2)
	v_mfma_f32_32x32x16_bf16 v[0:15], v[0:3], v[4:7], 0
	v_mov_b32_e32 v220, 0
	v_mov_b32_e32 v221, 0
	s_waitcnt lgkmcnt(0)
	v_mfma_f32_32x32x16_bf16 v[0:15], v[16:19], v[20:23], v[0:15]
	ds_read_b128 v[16:19], v152 offset:64
	ds_read_b128 v[20:23], v153 offset:64
	ds_read_u16 v199, v172
	ds_read_u16 v203, v172 offset:144
	ds_read_u16 v200, v172 offset:288
	ds_read_u16 v211, v172 offset:432
	ds_read_u16 v196, v172 offset:496
	ds_read_u16 v195, v172 offset:352
	ds_read_u16 v198, v172 offset:208
	ds_read_u16 v197, v172 offset:64
	ds_read_b128 v[24:27], v152 offset:96
	ds_read_b128 v[28:31], v153 offset:96
	ds_read_u16 v214, v172 offset:576
	ds_read_u16 v216, v172 offset:720
	ds_read_u16 v215, v172 offset:864
	ds_read_u16 v217, v172 offset:1008
	ds_read_u16 v202, v172 offset:1072
	ds_read_u16 v201, v172 offset:928
	ds_read_u16 v213, v172 offset:784
	ds_read_u16 v212, v172 offset:640
	s_waitcnt lgkmcnt(0)
	s_waitcnt lgkmcnt(14)
	v_mfma_f32_32x32x16_bf16 v[0:15], v[16:19], v[20:23], v[0:15]
	v_add_u32_e32 v16, v154, v173
	s_waitcnt lgkmcnt(8)
	v_mfma_f32_32x32x16_bf16 v[0:15], v[24:27], v[28:31], v[0:15]
	s_nop 11
	ds_write2_b32 v16, v0, v1 offset1:36
	v_add_u32_e32 v0, v154, v174
	ds_write2_b32 v0, v2, v3 offset1:36
	ds_write_b32 v0, v4 offset:864
	v_add_u32_e32 v0, 0x400, v16
	ds_write2_b32 v0, v5, v6 offset0:68 offset1:104
	v_add_u32_e32 v0, 0x600, v16
	ds_write2_b32 v0, v7, v8 offset0:12 offset1:192
	v_add_u32_e32 v0, 0x800, v16
	ds_write2_b32 v0, v9, v10 offset0:100 offset1:136
	v_add_u32_e32 v0, 0xa00, v16
	ds_write2_b32 v0, v11, v12 offset0:44 offset1:224
	v_add_u32_e32 v0, 0xc00, v16
	ds_write2_b32 v0, v13, v14 offset0:132 offset1:168
	ds_write_b32 v16, v15 offset:3888
	s_waitcnt lgkmcnt(0)
; #define LAS __attribute__((address_space(3)))
; __device__ __forceinline__ unsigned f2bf(float f) { return cvt_pk_bf16(f, f) & 0xffffu; }
; __device__ __forceinline__ void phase_rwkv_fused(const Frame& F, const Args& a, int l) {
;     ...
;         for (int t = 0; t < 16; ++t) y2[t] = (L < 16 && L < t) ? GL[t * GLD + 16 + (L & 15)] : 0.f;
; #pragma unroll
;         for (int t = 1; t < 16; ++t) {
;             float cf[16];
; #pragma unroll
;             for (int q = 0; q < 4; ++q) { if (4 * q < t) { const f32x4 c4 = *(const LAS f32x4*)(GL + t * GLD + 4 * q); cf[4 * q] = c4.x; cf[4 * q + 1] = c4.y; cf[4 * q + 2] = c4.z; cf[4 * q + 3] = c4.w; } }
; #pragma unroll
;             for (int s = 0; s < 16; ++s) if (s < t) { atf[t] += cf[s] * atf[s]; y2[t] += cf[s] * y2[s]; }
;         }
; #pragma unroll
;         for (int t = 0; t < 16; ++t) { AR[t * LDA + L] = (bf16)f2bf(atf[t]); if (L < 16) M2[t * M2D + L] = (bf16)f2bf(y2[t]); }
	s_and_saveexec_b64 s[16:17], s[34:35]
	ds_read_b32 v221, v175
	s_or_b64 exec, exec, s[16:17]
	v_mov_b32_e32 v222, 0
	s_mov_b64 s[16:17], exec
	v_readlane_b32 s22, v255, 31
	v_readlane_b32 s23, v255, 32
	s_and_b64 s[22:23], s[16:17], s[22:23]
	s_mov_b64 exec, s[22:23]
	ds_read_b32 v222, v176
	s_or_b64 exec, exec, s[16:17]
	s_mov_b64 s[16:17], exec
	v_readlane_b32 s22, v255, 33
	v_readlane_b32 s23, v255, 34
	s_and_b64 s[22:23], s[16:17], s[22:23]
	s_mov_b64 exec, s[22:23]
	ds_read_b32 v220, v177
	s_or_b64 exec, exec, s[16:17]
	v_mov_b32_e32 v223, 0
	v_mov_b32_e32 v224, 0
	s_mov_b64 s[16:17], exec
	v_readlane_b32 s22, v255, 35
	v_readlane_b32 s23, v255, 36
	s_and_b64 s[22:23], s[16:17], s[22:23]
	s_mov_b64 exec, s[22:23]
	ds_read_b32 v224, v178
	s_or_b64 exec, exec, s[16:17]
	s_mov_b64 s[16:17], exec
	v_readlane_b32 s22, v255, 37
	v_readlane_b32 s23, v255, 38
	s_and_b64 s[22:23], s[16:17], s[22:23]
	s_mov_b64 exec, s[22:23]
	ds_read_b32 v223, v179
	s_or_b64 exec, exec, s[16:17]
	v_mov_b32_e32 v227, 0
	v_mov_b32_e32 v228, 0
	s_and_saveexec_b64 s[16:17], s[44:45]
	ds_read_b32 v228, v180
	s_or_b64 exec, exec, s[16:17]
	s_and_saveexec_b64 s[16:17], s[46:47]
	ds_read_b32 v227, v181
	s_or_b64 exec, exec, s[16:17]
	v_mov_b32_e32 v232, 0
	v_mov_b32_e32 v233, 0
	s_and_saveexec_b64 s[16:17], s[48:49]
	ds_read_b32 v233, v182
	s_or_b64 exec, exec, s[16:17]
	s_and_saveexec_b64 s[16:17], s[50:51]
	ds_read_b32 v232, v183
	s_or_b64 exec, exec, s[16:17]
	v_mov_b32_e32 v236, 0
	v_mov_b32_e32 v237, 0
	s_and_saveexec_b64 s[16:17], s[52:53]
	ds_read_b32 v237, v184
	s_or_b64 exec, exec, s[16:17]
	s_and_saveexec_b64 s[16:17], s[54:55]
	ds_read_b32 v236, v186
	s_or_b64 exec, exec, s[16:17]
	v_mov_b32_e32 v238, 0
	v_mov_b32_e32 v240, 0
	s_and_saveexec_b64 s[16:17], s[56:57]
	ds_read_b32 v240, v188
	s_or_b64 exec, exec, s[16:17]
	s_and_saveexec_b64 s[16:17], s[58:59]
	ds_read_b32 v238, v189
	s_or_b64 exec, exec, s[16:17]
	v_mov_b32_e32 v243, 0
	v_mov_b32_e32 v245, 0
	s_and_saveexec_b64 s[16:17], s[60:61]
	ds_read_b32 v245, v190
	s_or_b64 exec, exec, s[16:17]
	s_and_saveexec_b64 s[16:17], s[62:63]
	ds_read_b32 v243, v191
	s_or_b64 exec, exec, s[16:17]
	v_readlane_b32 s16, v255, 39
	v_mov_b32_e32 v0, s68
	s_nop 0
	v_mov_b32_e32 v1, s16
	v_readlane_b32 s16, v255, 41
	ds_read_b128 v[140:143], v0
	ds_read_b128 v[136:139], v1
	v_mov_b32_e32 v0, s16
	v_readlane_b32 s16, v255, 43
	s_nop 1
	v_mov_b32_e32 v1, s16
	v_readlane_b32 s16, v255, 45
	ds_read_b128 v[132:135], v0
	ds_read_b128 v[128:131], v1
	v_mov_b32_e32 v0, s16
	v_readlane_b32 s16, v255, 47
	s_nop 1
	v_mov_b32_e32 v1, s16
	v_readlane_b32 s16, v255, 49
	ds_read_b128 v[124:127], v0
	ds_read_b128 v[120:123], v1
	v_mov_b32_e32 v0, s16
	v_readlane_b32 s16, v255, 51
	s_nop 1
	v_mov_b32_e32 v1, s16
	ds_read_b128 v[116:119], v0
	ds_read_b128 v[112:115], v1
	v_mov_b32_e32 v0, s26
	v_mov_b32_e32 v1, s27
	ds_read_b128 v[108:111], v0
	ds_read_b128 v[104:107], v1
	v_mov_b32_e32 v0, s28
	v_mov_b32_e32 v1, s29
	ds_read_b128 v[100:103], v0
	ds_read_b128 v[96:99], v1
	v_mov_b32_e32 v0, s30
	v_mov_b32_e32 v1, s31
	ds_read_b128 v[92:95], v0
	ds_read_b128 v[84:87], v1
	v_mov_b32_e32 v0, s6
	v_mov_b32_e32 v1, s7
	ds_read_b128 v[88:91], v0
	ds_read_b128 v[80:83], v1
	v_mov_b32_e32 v0, s8
	v_mov_b32_e32 v1, s9
	ds_read_b128 v[76:79], v0
	ds_read_b128 v[72:75], v1
	v_mov_b32_e32 v0, s10
	v_mov_b32_e32 v1, s11
	ds_read_b128 v[68:71], v0
	ds_read_b128 v[64:67], v1
	v_mov_b32_e32 v0, s12
	v_mov_b32_e32 v1, s13
	ds_read_b128 v[60:63], v0
	ds_read_b128 v[56:59], v1
	v_mov_b32_e32 v0, s14
	v_mov_b32_e32 v1, s15
	ds_read_b128 v[52:55], v0
	ds_read_b128 v[48:51], v1
	v_mov_b32_e32 v0, s64
	v_mov_b32_e32 v1, s65
	ds_read_b128 v[44:47], v0
	ds_read_b128 v[40:43], v1
	v_mov_b32_e32 v0, s66
	v_mov_b32_e32 v1, s67
	ds_read_b128 v[32:35], v0
	ds_read_b128 v[36:39], v1
	v_mov_b32_e32 v0, s18
	v_mov_b32_e32 v1, s19
	ds_read_b128 v[28:31], v0
	ds_read_b128 v[24:27], v1
	v_mov_b32_e32 v0, s70
	v_mov_b32_e32 v1, s71
	ds_read_b128 v[20:23], v0
	ds_read_b128 v[16:19], v1
	v_mov_b32_e32 v0, s86
	v_mov_b32_e32 v1, s87
	ds_read_b128 v[12:15], v0
	ds_read_b128 v[8:11], v1
	v_mov_b32_e32 v0, s20
	v_mov_b32_e32 v1, s21
	ds_read_b128 v[4:7], v0
	ds_read_b128 v[0:3], v1
	s_waitcnt lgkmcnt(14)
	v_fma_f32 v63, -v140, v218, v234
	s_waitcnt lgkmcnt(0)
	v_fma_f32 v3, -v136, v218, v241
	v_fmac_f32_e32 v3, v137, v63
	ds_write_b16 v155, v230
	s_and_saveexec_b64 s[16:17], s[4:5]
	s_xor_b64 s[16:17], exec, s[16:17]
	s_cbranch_execz .LBB0_669
	v_cvt_pk_bf16_f32 v18, v63, v3
	ds_write_b16 v155, v18 offset:144
	ds_write_b16_d16_hi v155, v18 offset:288
.LBB0_669:
	s_or_saveexec_b64 s[72:73], s[16:17]
	v_fmac_f32_e32 v221, 0, v140
	v_fmac_f32_e32 v222, 0, v136
	v_fmac_f32_e32 v220, 0, v132
	v_fmac_f32_e32 v222, v137, v221
	v_fmac_f32_e32 v220, v133, v221
	v_fmac_f32_e32 v220, v134, v222
	s_xor_b64 exec, exec, s[72:73]
	s_cbranch_execz .LBB0_671
	v_cvt_pk_bf16_f32 v18, v221, v63
	ds_write_b16 v156, v18 offset:48
	ds_write_b16_d16_hi v155, v18 offset:144
	v_cvt_pk_bf16_f32 v18, v3, v222
	ds_write_b16 v155, v18 offset:288
	ds_write_b16_d16_hi v156, v18 offset:96
	v_cvt_pk_bf16_f32 v18, v220, s0
	ds_write_b16 v156, v185
	ds_write_b16 v156, v18 offset:144
; #define LAS __attribute__((address_space(3)))
; __device__ __forceinline__ unsigned f2bf(float f) { return cvt_pk_bf16(f, f) & 0xffffu; }
; __device__ __forceinline__ void phase_rwkv_fused(const Frame& F, const Args& a, int l) {
;     ...
; #pragma unroll
;         for (int t = 1; t < 16; ++t) {
;             float cf[16];
; #pragma unroll
;             for (int q = 0; q < 4; ++q) { if (4 * q < t) { const f32x4 c4 = *(const LAS f32x4*)(GL + t * GLD + 4 * q); cf[4 * q] = c4.x; cf[4 * q + 1] = c4.y; cf[4 * q + 2] = c4.z; cf[4 * q + 3] = c4.w; } }
; #pragma unroll
;             for (int s = 0; s < 16; ++s) if (s < t) { atf[t] += cf[s] * atf[s]; y2[t] += cf[s] * y2[s]; }
;         }
; #pragma unroll
;         for (int t = 0; t < 16; ++t) { AR[t * LDA + L] = (bf16)f2bf(atf[t]); if (L < 16) M2[t * M2D + L] = (bf16)f2bf(y2[t]); }
.LBB0_671:
	s_or_b64 exec, exec, s[72:73]
	v_fma_f32 v74, -v132, v218, v235
	v_fma_f32 v75, -v128, v218, v244
	v_fma_f32 v89, -v124, v218, v247
	v_fma_f32 v90, -v116, v218, v249
	v_fmac_f32_e32 v74, v133, v63
	v_fmac_f32_e32 v75, v63, v129
	v_fmac_f32_e32 v89, v63, v125
	v_fmac_f32_e32 v90, v63, v117
	v_fmac_f32_e32 v74, v134, v3
	v_fmac_f32_e32 v75, v130, v3
	v_fmac_f32_e32 v89, v126, v3
	v_fmac_f32_e32 v90, v3, v118
	v_fmac_f32_e32 v75, v131, v74
	v_fmac_f32_e32 v89, v127, v74
	v_fmac_f32_e32 v90, v119, v74
	v_fmac_f32_e32 v89, v120, v75
	v_fmac_f32_e32 v90, v112, v75
	v_cvt_pk_bf16_f32 v18, v74, s0
	v_fmac_f32_e32 v90, v113, v89
	ds_write_b16 v155, v18 offset:432
	v_cvt_pk_bf16_f32 v18, v75, s0
	ds_write_b16 v155, v18 offset:576
	s_and_saveexec_b64 s[16:17], s[4:5]
	s_xor_b64 s[16:17], exec, s[16:17]
	s_cbranch_execz .LBB0_673
	v_cvt_pk_bf16_f32 v18, v89, v90
	ds_write_b16 v155, v18 offset:720
	ds_write_b16_d16_hi v155, v18 offset:864
.LBB0_673:
	s_or_saveexec_b64 s[72:73], s[16:17]
	v_fmac_f32_e32 v224, 0, v128
	v_fmac_f32_e32 v223, 0, v124
	v_fmac_f32_e32 v228, 0, v116
	v_fmac_f32_e32 v227, 0, v108
	v_fmac_f32_e32 v224, v221, v129
	v_fmac_f32_e32 v223, v221, v125
	v_fmac_f32_e32 v228, v221, v117
	v_fmac_f32_e32 v227, v221, v109
	v_fmac_f32_e32 v224, v130, v222
	v_fmac_f32_e32 v223, v126, v222
	v_fmac_f32_e32 v228, v222, v118
	v_fmac_f32_e32 v227, v222, v110
	v_fmac_f32_e32 v224, v131, v220
	v_fmac_f32_e32 v223, v127, v220
	v_fmac_f32_e32 v228, v119, v220
	v_fmac_f32_e32 v227, v220, v111
	v_fmac_f32_e32 v223, v120, v224
	v_fmac_f32_e32 v228, v112, v224
	v_fmac_f32_e32 v227, v224, v104
	v_fmac_f32_e32 v228, v113, v223
	v_fmac_f32_e32 v227, v105, v223
	v_fmac_f32_e32 v227, v106, v228
	s_xor_b64 exec, exec, s[72:73]
	s_cbranch_execz .LBB0_675
	v_cvt_pk_bf16_f32 v18, v224, v223
	ds_write_b16 v156, v18 offset:192
	ds_write_b16_d16_hi v156, v18 offset:240
	v_cvt_pk_bf16_f32 v18, v89, v90
	ds_write_b16 v155, v18 offset:720
	ds_write_b16_d16_hi v155, v18 offset:864
	v_cvt_pk_bf16_f32 v18, v228, v227
	ds_write_b16 v156, v18 offset:288
	ds_write_b16_d16_hi v156, v18 offset:336
.LBB0_675:
	s_or_b64 exec, exec, s[72:73]
	v_fma_f32 v91, -v108, v218, v239
	v_fmac_f32_e32 v91, v63, v109
	v_fmac_f32_e32 v91, v3, v110
	v_fmac_f32_e32 v91, v74, v111
	v_fmac_f32_e32 v91, v75, v104
	v_fmac_f32_e32 v91, v105, v89
	v_fmac_f32_e32 v91, v106, v90
	v_fma_f32 v104, -v100, v218, v242
	v_fma_f32 v105, -v92, v218, v246
	v_fma_f32 v106, -v80, v218, v248
	v_fmac_f32_e32 v104, v63, v101
	v_fmac_f32_e32 v105, v63, v93
	v_fmac_f32_e32 v106, v63, v81
	v_fmac_f32_e32 v104, v3, v102
	v_fmac_f32_e32 v105, v3, v94
	v_fmac_f32_e32 v106, v3, v82
	v_fmac_f32_e32 v104, v74, v103
	v_fmac_f32_e32 v105, v74, v95
	v_fmac_f32_e32 v106, v74, v83
	v_fmac_f32_e32 v104, v75, v96
	v_fmac_f32_e32 v105, v75, v84
	v_fmac_f32_e32 v106, v75, v76
	v_fmac_f32_e32 v104, v89, v97
	v_fmac_f32_e32 v105, v89, v85
	v_fmac_f32_e32 v106, v89, v77
	v_fmac_f32_e32 v104, v98, v90
	v_fmac_f32_e32 v105, v86, v90
	v_fmac_f32_e32 v106, v90, v78
	v_fmac_f32_e32 v104, v99, v91
	v_fmac_f32_e32 v105, v87, v91
	v_fmac_f32_e32 v106, v79, v91
	v_fmac_f32_e32 v105, v88, v104
	v_fmac_f32_e32 v106, v72, v104
	v_cvt_pk_bf16_f32 v18, v91, s0
	v_fmac_f32_e32 v106, v73, v105
	ds_write_b16 v155, v18 offset:1008
	v_cvt_pk_bf16_f32 v18, v104, s0
	ds_write_b16 v155, v18 offset:1152
	s_and_saveexec_b64 s[16:17], s[4:5]
	s_xor_b64 s[16:17], exec, s[16:17]
	s_cbranch_execz .LBB0_677
	v_cvt_pk_bf16_f32 v18, v105, v106
	ds_write_b16 v155, v18 offset:1296
	ds_write_b16_d16_hi v155, v18 offset:1440
.LBB0_677:
	s_or_saveexec_b64 s[72:73], s[16:17]
	v_fmac_f32_e32 v233, 0, v100
	v_fmac_f32_e32 v232, 0, v92
	v_fmac_f32_e32 v237, 0, v80
	v_fmac_f32_e32 v236, 0, v68
	v_fmac_f32_e32 v233, v221, v101
	v_fmac_f32_e32 v232, v221, v93
	v_fmac_f32_e32 v237, v221, v81
	v_fmac_f32_e32 v236, v221, v69
	v_fmac_f32_e32 v233, v222, v102
	v_fmac_f32_e32 v232, v222, v94
	v_fmac_f32_e32 v237, v222, v82
	v_fmac_f32_e32 v236, v222, v70
	v_fmac_f32_e32 v233, v220, v103
	v_fmac_f32_e32 v232, v220, v95
	v_fmac_f32_e32 v237, v220, v83
	v_fmac_f32_e32 v236, v220, v71
	v_fmac_f32_e32 v233, v224, v96
	v_fmac_f32_e32 v232, v224, v84
	v_fmac_f32_e32 v237, v224, v76
	v_fmac_f32_e32 v236, v224, v64
	v_fmac_f32_e32 v233, v223, v97
	v_fmac_f32_e32 v232, v223, v85
	v_fmac_f32_e32 v237, v223, v77
	v_fmac_f32_e32 v236, v223, v65
	v_fmac_f32_e32 v233, v98, v228
	v_fmac_f32_e32 v232, v86, v228
	v_fmac_f32_e32 v237, v228, v78
	v_fmac_f32_e32 v236, v228, v66
	v_fmac_f32_e32 v233, v99, v227
	v_fmac_f32_e32 v232, v87, v227
	v_fmac_f32_e32 v237, v79, v227
	v_fmac_f32_e32 v236, v227, v67
	v_fmac_f32_e32 v232, v88, v233
	v_fmac_f32_e32 v237, v72, v233
	v_fmac_f32_e32 v236, v233, v60
	v_fmac_f32_e32 v237, v73, v232
	v_fmac_f32_e32 v236, v61, v232
	v_fmac_f32_e32 v236, v62, v237
	s_xor_b64 exec, exec, s[72:73]
	s_cbranch_execz .LBB0_679
	v_cvt_pk_bf16_f32 v18, v233, v232
	ds_write_b16 v156, v18 offset:384
	ds_write_b16_d16_hi v156, v18 offset:432
	v_cvt_pk_bf16_f32 v18, v105, v106
	ds_write_b16 v155, v18 offset:1296
	ds_write_b16_d16_hi v155, v18 offset:1440
	v_cvt_pk_bf16_f32 v18, v237, v236
	ds_write_b16 v156, v18 offset:480
	ds_write_b16_d16_hi v156, v18 offset:528
; #define LAS __attribute__((address_space(3)))
; __device__ __forceinline__ unsigned f2bf(float f) { return cvt_pk_bf16(f, f) & 0xffffu; }
; __device__ __forceinline__ void phase_rwkv_fused(const Frame& F, const Args& a, int l) {
;     ...
; #pragma unroll
;         for (int t = 1; t < 16; ++t) {
;             float cf[16];
; #pragma unroll
;             for (int q = 0; q < 4; ++q) { if (4 * q < t) { const f32x4 c4 = *(const LAS f32x4*)(GL + t * GLD + 4 * q); cf[4 * q] = c4.x; cf[4 * q + 1] = c4.y; cf[4 * q + 2] = c4.z; cf[4 * q + 3] = c4.w; } }
; #pragma unroll
;             for (int s = 0; s < 16; ++s) if (s < t) { atf[t] += cf[s] * atf[s]; y2[t] += cf[s] * y2[s]; }
;         }
; #pragma unroll
;         for (int t = 0; t < 16; ++t) { AR[t * LDA + L] = (bf16)f2bf(atf[t]); if (L < 16) M2[t * M2D + L] = (bf16)f2bf(y2[t]); }
.LBB0_679:
	s_or_b64 exec, exec, s[72:73]
	v_fma_f32 v68, -v68, v218, v225
	v_fmac_f32_e32 v68, v63, v69
	v_fmac_f32_e32 v68, v3, v70
	v_fmac_f32_e32 v68, v74, v71
	v_fmac_f32_e32 v68, v75, v64
	v_fmac_f32_e32 v68, v89, v65
	v_fmac_f32_e32 v68, v90, v66
	v_fmac_f32_e32 v68, v91, v67
	v_fmac_f32_e32 v68, v104, v60
	v_fmac_f32_e32 v68, v61, v105
	v_fmac_f32_e32 v68, v62, v106
	v_fma_f32 v60, -v56, v218, v226
	v_fma_f32 v61, -v44, v218, v229
	v_fma_f32 v62, -v28, v218, v231
	v_fmac_f32_e32 v60, v63, v57
	v_fmac_f32_e32 v61, v63, v45
	v_fmac_f32_e32 v62, v63, v29
	v_fmac_f32_e32 v60, v3, v58
	v_fmac_f32_e32 v61, v3, v46
	v_fmac_f32_e32 v62, v3, v30
	v_fmac_f32_e32 v60, v74, v59
	v_fmac_f32_e32 v61, v74, v47
	v_fmac_f32_e32 v62, v74, v31
	v_fmac_f32_e32 v60, v75, v52
	v_fmac_f32_e32 v61, v75, v40
	v_fmac_f32_e32 v62, v75, v24
	v_fmac_f32_e32 v60, v89, v53
	v_fmac_f32_e32 v61, v89, v41
	v_fmac_f32_e32 v62, v89, v25
	v_fmac_f32_e32 v60, v90, v54
	v_fmac_f32_e32 v61, v90, v42
	v_fmac_f32_e32 v62, v90, v26
	v_fmac_f32_e32 v60, v91, v55
	v_fmac_f32_e32 v61, v91, v43
	v_fmac_f32_e32 v62, v91, v27
	v_fmac_f32_e32 v60, v104, v48
	v_fmac_f32_e32 v61, v104, v32
	v_fmac_f32_e32 v62, v104, v20
	v_fmac_f32_e32 v60, v105, v49
	v_fmac_f32_e32 v61, v105, v33
	v_fmac_f32_e32 v62, v105, v21
	v_fmac_f32_e32 v60, v50, v106
	v_fmac_f32_e32 v61, v34, v106
	v_fmac_f32_e32 v62, v106, v22
	v_fmac_f32_e32 v60, v51, v68
	v_fmac_f32_e32 v61, v35, v68
	v_fmac_f32_e32 v62, v23, v68
	v_fmac_f32_e32 v61, v36, v60
	v_fmac_f32_e32 v62, v16, v60
	v_cvt_pk_bf16_f32 v18, v68, s0
	v_fmac_f32_e32 v62, v17, v61
	ds_write_b16 v155, v18 offset:1584
	v_cvt_pk_bf16_f32 v18, v60, s0
	ds_write_b16 v155, v18 offset:1728
	s_and_saveexec_b64 s[16:17], s[4:5]
	s_xor_b64 s[72:73], exec, s[16:17]
	s_cbranch_execz .LBB0_681
	v_cvt_pk_bf16_f32 v16, v61, v62
	ds_write_b16 v155, v16 offset:1872
	ds_write_b16_d16_hi v155, v16 offset:2016
.LBB0_681:
	s_andn2_saveexec_b64 s[72:73], s[72:73]
	s_cbranch_execz .LBB0_683
	v_fmac_f32_e32 v240, 0, v56
	v_fmac_f32_e32 v238, 0, v44
	v_fmac_f32_e32 v245, 0, v28
	v_fmac_f32_e32 v240, v221, v57
	v_fmac_f32_e32 v238, v221, v45
	v_fmac_f32_e32 v245, v221, v29
	v_fmac_f32_e32 v240, v222, v58
	v_fmac_f32_e32 v238, v222, v46
	v_fmac_f32_e32 v245, v222, v30
	v_fmac_f32_e32 v243, 0, v12
	v_fmac_f32_e32 v240, v220, v59
	v_fmac_f32_e32 v238, v220, v47
	v_fmac_f32_e32 v245, v220, v31
	v_fmac_f32_e32 v243, v221, v13
	v_fmac_f32_e32 v240, v224, v52
	v_fmac_f32_e32 v238, v224, v40
	v_fmac_f32_e32 v245, v224, v24
	v_fmac_f32_e32 v243, v222, v14
	v_fmac_f32_e32 v240, v223, v53
	v_fmac_f32_e32 v238, v223, v41
	v_fmac_f32_e32 v245, v223, v25
	v_fmac_f32_e32 v243, v220, v15
	v_fmac_f32_e32 v240, v228, v54
	v_fmac_f32_e32 v238, v228, v42
	v_fmac_f32_e32 v245, v228, v26
	v_fmac_f32_e32 v243, v224, v8
	v_fmac_f32_e32 v240, v227, v55
	v_fmac_f32_e32 v238, v227, v43
	v_fmac_f32_e32 v245, v227, v27
	v_fmac_f32_e32 v243, v223, v9
	v_fmac_f32_e32 v240, v233, v48
	v_fmac_f32_e32 v238, v233, v32
	v_fmac_f32_e32 v245, v233, v20
	v_fmac_f32_e32 v243, v228, v10
	v_fmac_f32_e32 v240, v232, v49
	v_fmac_f32_e32 v238, v232, v33
	v_fmac_f32_e32 v245, v232, v21
	v_fmac_f32_e32 v243, v227, v11
	v_fmac_f32_e32 v240, v50, v237
	v_fmac_f32_e32 v238, v34, v237
	v_fmac_f32_e32 v245, v237, v22
	v_fmac_f32_e32 v243, v233, v4
	v_fmac_f32_e32 v240, v51, v236
	v_fmac_f32_e32 v238, v35, v236
	v_fmac_f32_e32 v245, v23, v236
	v_fmac_f32_e32 v243, v232, v5
	v_fmac_f32_e32 v238, v36, v240
	v_fmac_f32_e32 v245, v16, v240
	v_fmac_f32_e32 v243, v237, v6
	v_cvt_pk_bf16_f32 v16, v240, s0
	v_fmac_f32_e32 v243, v236, v7
	ds_write_b16 v156, v16 offset:576
	v_cvt_pk_bf16_f32 v16, v238, s0
	v_fmac_f32_e32 v243, v240, v0
	ds_write_b16 v156, v16 offset:624
	v_cvt_pk_bf16_f32 v16, v61, s0
	v_fmac_f32_e32 v245, v17, v238
	v_fmac_f32_e32 v243, v1, v238
	ds_write_b16 v155, v16 offset:1872
	v_cvt_pk_bf16_f32 v16, v62, s0
	v_fmac_f32_e32 v243, v2, v245
	ds_write_b16 v155, v16 offset:2016
	v_cvt_pk_bf16_f32 v16, v245, v243
	ds_write_b16 v156, v16 offset:672
	ds_write_b16_d16_hi v156, v16 offset:720
